# NSA sliding-window epilogue de-serialised: 16 accb loads hoisted and issued together (counted vmcnt) instead of load/wait(0)/store per group; on top of v36
# speedup vs baseline: 1.0338x; 1.0139x over previous
; __device__ __forceinline__ u32x2 pack4(f32x4 v) { u32x2 w; w.x = cvtpk(v[0], v[1]); w.y = cvtpk(v[2], v[3]); return w; }
; __device__ __forceinline__ unsigned pack4_fp8(float a, float b, float c, float d) { unsigned w = 0u; w = (unsigned)__builtin_amdgcn_cvt_pk_fp8_f32(a, b, (int)w, false); w = (unsigned)__builtin_amdgcn_cvt_pk_fp8_f32(c, d, (int)w, true); return w; }
; __device__ __forceinline__ void nsa_unit(Frame& F, int b, int g, int c) {
;     ...
;     { const float sc = l > 0.f ? gw / l : 0.f; unsigned char* orow = ws + WS_H + ((((trow >> 8) * 32) + hg) * 256 + (trow & 255)) * 128;
; #pragma unroll
;       for (int db = 0; db < 4; ++db)
; #pragma unroll
;           for (int q4 = 0; q4 < 4; ++q4) { const bf16_t* p = accb + 32 * db + 8 * q4 + 4 * hi; f32x4 o = {O[db][4 * q4], O[db][4 * q4 + 1], O[db][4 * q4 + 2], O[db][4 * q4 + 3]}; const u32x2 w = *(const u32x2*)p;
;               const f32x4 pr = {__uint_as_float(w.x << 16), __uint_as_float(w.x & 0xffff0000u), __uint_as_float(w.y << 16), __uint_as_float(w.y & 0xffff0000u)};
;               const f32x4 r = pr + o * sc;
;               if constexpr (FP8_OUT) *(unsigned*)(orow + 32 * db + 8 * q4 + 4 * hi) = pack4_fp8(r[0] * 16.0f, r[1] * 16.0f, r[2] * 16.0f, r[3] * 16.0f);
;               else *(u32x2*)((bf16_t*)(ws + WS_H) + trow * 4096 + hg * 128 + 32 * db + 8 * q4 + 4 * hi) = pack4(r); } }
.LBB0_839:
	global_load_dwordx2 v[220:221], v[160:161], off
	global_load_dwordx2 v[222:223], v[160:161], off offset:16
	global_load_dwordx2 v[224:225], v[160:161], off offset:32
	global_load_dwordx2 v[226:227], v[160:161], off offset:48
	global_load_dwordx2 v[228:229], v[160:161], off offset:64
	global_load_dwordx2 v[230:231], v[160:161], off offset:80
	global_load_dwordx2 v[232:233], v[160:161], off offset:96
	global_load_dwordx2 v[234:235], v[160:161], off offset:112
	global_load_dwordx2 v[236:237], v[160:161], off offset:128
	global_load_dwordx2 v[238:239], v[160:161], off offset:144
	global_load_dwordx2 v[240:241], v[160:161], off offset:160
	global_load_dwordx2 v[242:243], v[160:161], off offset:176
	global_load_dwordx2 v[246:247], v[160:161], off offset:192
	global_load_dwordx2 v[248:249], v[160:161], off offset:208
	global_load_dwordx2 v[250:251], v[160:161], off offset:224
	global_load_dwordx2 v[252:253], v[160:161], off offset:240
	v_div_scale_f32 v66, s[0:1], v67, v67, v148
	v_rcp_f32_e32 v75, v66
	v_lshlrev_b32_e32 v73, 7, v154
	v_and_b32_e32 v150, 0x7f80, v73
	v_div_scale_f32 v72, vcc, v148, v67, v148
	v_fma_f32 v73, -v66, v75, 1.0
	v_fmac_f32_e32 v75, v73, v75
	v_mul_f32_e32 v73, v72, v75
	v_fma_f32 v76, -v66, v73, v72
	v_fmac_f32_e32 v73, v76, v75
	v_fma_f32 v66, -v66, v73, v72
	v_div_fmas_f32 v66, v66, v75, v73
	v_div_fixup_f32 v66, v66, v67, v148
	v_cmp_lt_f32_e32 vcc, 0, v67
	v_mov_b32_e32 v74, v151
	v_lshrrev_b64 v[70:71], 3, v[156:157]
	v_cndmask_b32_e32 v66, 0, v66, vcc
	s_movk_i32 s0, 0xffe0
	v_and_b32_e32 v71, 0x1ffff, v71
	v_and_or_b32 v70, v70, s0, v149
	v_readlane_b32 s0, v245, 61
	v_lshlrev_b64 v[70:71], 15, v[70:71]
	v_readlane_b32 s1, v245, 62
	s_and_b64 vcc, exec, s[96:97]
	s_waitcnt vmcnt(15)
	v_lshlrev_b32_e32 v72, 16, v220
	v_and_b32_e32 v73, 0xffff0000, v220
	v_pk_fma_f32 v[50:51], v[66:67], v[50:51], v[72:73] op_sel_hi:[0,1,1]
	v_mul_f32_e32 v50, 0x41800000, v50
	v_mul_f32_e32 v51, 0x41800000, v51
	v_cvt_pk_fp8_f32 v74, v50, v51
	v_lshlrev_b32_e32 v68, 16, v221
	v_and_b32_e32 v69, 0xffff0000, v221
	v_pk_fma_f32 v[50:51], v[66:67], v[52:53], v[68:69] op_sel_hi:[0,1,1]
	v_mul_f32_e32 v50, 0x41800000, v50
	v_mul_f32_e32 v51, 0x41800000, v51
	v_cvt_pk_fp8_f32 v74, v50, v51 op_sel:[0,0,1]
	v_lshl_add_u64 v[50:51], s[0:1], 0, v[70:71]
	v_lshl_add_u64 v[50:51], v[50:51], 0, v[150:151]
	v_lshl_add_u64 v[50:51], v[50:51], 0, v[158:159]
	global_store_dword v[50:51], v74, off
	v_mov_b32_e32 v67, v151
	s_mov_b64 s[0:1], 0
	s_waitcnt vmcnt(15)
	v_lshlrev_b32_e32 v68, 16, v222
	v_and_b32_e32 v69, 0xffff0000, v222
	v_pk_fma_f32 v[54:55], v[66:67], v[54:55], v[68:69] op_sel_hi:[0,1,1]
	v_mul_f32_e32 v54, 0x41800000, v54
	v_mul_f32_e32 v55, 0x41800000, v55
	v_cvt_pk_fp8_f32 v67, v54, v55
	v_lshlrev_b32_e32 v52, 16, v223
	v_and_b32_e32 v53, 0xffff0000, v223
	v_pk_fma_f32 v[52:53], v[66:67], v[56:57], v[52:53] op_sel_hi:[0,1,1]
	v_mul_f32_e32 v52, 0x41800000, v52
	v_mul_f32_e32 v53, 0x41800000, v53
	v_cvt_pk_fp8_f32 v67, v52, v53 op_sel:[0,0,1]
	v_mov_b32_e32 v56, v151
	global_store_dword v[50:51], v67, off offset:8
	s_waitcnt vmcnt(15)
	v_lshlrev_b32_e32 v54, 16, v224
	v_and_b32_e32 v55, 0xffff0000, v224
	v_pk_fma_f32 v[54:55], v[66:67], v[58:59], v[54:55] op_sel_hi:[0,1,1]
	v_mul_f32_e32 v54, 0x41800000, v54
	v_mul_f32_e32 v55, 0x41800000, v55
	v_cvt_pk_fp8_f32 v56, v54, v55
	v_lshlrev_b32_e32 v52, 16, v225
	v_and_b32_e32 v53, 0xffff0000, v225
	v_pk_fma_f32 v[52:53], v[66:67], v[60:61], v[52:53] op_sel_hi:[0,1,1]
	v_mul_f32_e32 v52, 0x41800000, v52
	v_mul_f32_e32 v53, 0x41800000, v53
	v_cvt_pk_fp8_f32 v56, v52, v53 op_sel:[0,0,1]
	global_store_dword v[50:51], v56, off offset:16
	v_mov_b32_e32 v56, v151
	s_waitcnt vmcnt(15)
	v_lshlrev_b32_e32 v54, 16, v226
	v_and_b32_e32 v55, 0xffff0000, v226
	v_pk_fma_f32 v[54:55], v[66:67], v[62:63], v[54:55] op_sel_hi:[0,1,1]
	v_mul_f32_e32 v54, 0x41800000, v54
	v_mul_f32_e32 v55, 0x41800000, v55
	v_cvt_pk_fp8_f32 v56, v54, v55
	v_lshlrev_b32_e32 v52, 16, v227
	v_and_b32_e32 v53, 0xffff0000, v227
	v_pk_fma_f32 v[52:53], v[66:67], v[64:65], v[52:53] op_sel_hi:[0,1,1]
	v_mul_f32_e32 v52, 0x41800000, v52
	v_mul_f32_e32 v53, 0x41800000, v53
	v_cvt_pk_fp8_f32 v56, v52, v53 op_sel:[0,0,1]
	global_store_dword v[50:51], v56, off offset:24
	v_mov_b32_e32 v56, v151
	s_waitcnt vmcnt(15)
	v_lshlrev_b32_e32 v54, 16, v228
	v_and_b32_e32 v55, 0xffff0000, v228
	v_pk_fma_f32 v[34:35], v[66:67], v[34:35], v[54:55] op_sel_hi:[0,1,1]
	v_mul_f32_e32 v34, 0x41800000, v34
	v_mul_f32_e32 v35, 0x41800000, v35
	v_cvt_pk_fp8_f32 v56, v34, v35
	v_lshlrev_b32_e32 v52, 16, v229
	v_and_b32_e32 v53, 0xffff0000, v229
	v_pk_fma_f32 v[34:35], v[66:67], v[36:37], v[52:53] op_sel_hi:[0,1,1]
	v_mul_f32_e32 v34, 0x41800000, v34
	v_mul_f32_e32 v35, 0x41800000, v35
	v_cvt_pk_fp8_f32 v56, v34, v35 op_sel:[0,0,1]
	v_mov_b32_e32 v52, v151
	global_store_dword v[50:51], v56, off offset:32
	s_waitcnt vmcnt(15)
	v_lshlrev_b32_e32 v36, 16, v230
	v_and_b32_e32 v37, 0xffff0000, v230
	v_pk_fma_f32 v[36:37], v[66:67], v[38:39], v[36:37] op_sel_hi:[0,1,1]
	v_mul_f32_e32 v36, 0x41800000, v36
	v_mul_f32_e32 v37, 0x41800000, v37
	v_cvt_pk_fp8_f32 v52, v36, v37
	v_lshlrev_b32_e32 v34, 16, v231
	v_and_b32_e32 v35, 0xffff0000, v231
	v_pk_fma_f32 v[34:35], v[66:67], v[40:41], v[34:35] op_sel_hi:[0,1,1]
	v_mul_f32_e32 v34, 0x41800000, v34
	v_mul_f32_e32 v35, 0x41800000, v35
	v_cvt_pk_fp8_f32 v52, v34, v35 op_sel:[0,0,1]
	v_mov_b32_e32 v38, v151
	global_store_dword v[50:51], v52, off offset:40
	s_waitcnt vmcnt(15)
; __device__ __forceinline__ u32x2 pack4(f32x4 v) { u32x2 w; w.x = cvtpk(v[0], v[1]); w.y = cvtpk(v[2], v[3]); return w; }
; __device__ __forceinline__ unsigned pack4_fp8(float a, float b, float c, float d) { unsigned w = 0u; w = (unsigned)__builtin_amdgcn_cvt_pk_fp8_f32(a, b, (int)w, false); w = (unsigned)__builtin_amdgcn_cvt_pk_fp8_f32(c, d, (int)w, true); return w; }
; __device__ __forceinline__ void nsa_unit(Frame& F, int b, int g, int c) {
;     ...
;     { const float sc = l > 0.f ? gw / l : 0.f; unsigned char* orow = ws + WS_H + ((((trow >> 8) * 32) + hg) * 256 + (trow & 255)) * 128;
; #pragma unroll
;       for (int db = 0; db < 4; ++db)
; #pragma unroll
;           for (int q4 = 0; q4 < 4; ++q4) { const bf16_t* p = accb + 32 * db + 8 * q4 + 4 * hi; f32x4 o = {O[db][4 * q4], O[db][4 * q4 + 1], O[db][4 * q4 + 2], O[db][4 * q4 + 3]}; const u32x2 w = *(const u32x2*)p;
;               const f32x4 pr = {__uint_as_float(w.x << 16), __uint_as_float(w.x & 0xffff0000u), __uint_as_float(w.y << 16), __uint_as_float(w.y & 0xffff0000u)};
;               const f32x4 r = pr + o * sc;
;               if constexpr (FP8_OUT) *(unsigned*)(orow + 32 * db + 8 * q4 + 4 * hi) = pack4_fp8(r[0] * 16.0f, r[1] * 16.0f, r[2] * 16.0f, r[3] * 16.0f);
;               else *(u32x2*)((bf16_t*)(ws + WS_H) + trow * 4096 + hg * 128 + 32 * db + 8 * q4 + 4 * hi) = pack4(r); } }
	v_lshlrev_b32_e32 v36, 16, v232
	v_and_b32_e32 v37, 0xffff0000, v232
	v_pk_fma_f32 v[36:37], v[66:67], v[42:43], v[36:37] op_sel_hi:[0,1,1]
	v_mul_f32_e32 v36, 0x41800000, v36
	v_mul_f32_e32 v37, 0x41800000, v37
	v_cvt_pk_fp8_f32 v38, v36, v37
	v_lshlrev_b32_e32 v34, 16, v233
	v_and_b32_e32 v35, 0xffff0000, v233
	v_pk_fma_f32 v[34:35], v[66:67], v[44:45], v[34:35] op_sel_hi:[0,1,1]
	v_mul_f32_e32 v34, 0x41800000, v34
	v_mul_f32_e32 v35, 0x41800000, v35
	v_cvt_pk_fp8_f32 v38, v34, v35 op_sel:[0,0,1]
	global_store_dword v[50:51], v38, off offset:48
	v_mov_b32_e32 v38, v151
	s_waitcnt vmcnt(15)
	v_lshlrev_b32_e32 v36, 16, v234
	v_and_b32_e32 v37, 0xffff0000, v234
	v_pk_fma_f32 v[36:37], v[66:67], v[46:47], v[36:37] op_sel_hi:[0,1,1]
	v_mul_f32_e32 v36, 0x41800000, v36
	v_mul_f32_e32 v37, 0x41800000, v37
	v_cvt_pk_fp8_f32 v38, v36, v37
	v_lshlrev_b32_e32 v34, 16, v235
	v_and_b32_e32 v35, 0xffff0000, v235
	v_pk_fma_f32 v[34:35], v[66:67], v[48:49], v[34:35] op_sel_hi:[0,1,1]
	v_mul_f32_e32 v34, 0x41800000, v34
	v_mul_f32_e32 v35, 0x41800000, v35
	v_cvt_pk_fp8_f32 v38, v34, v35 op_sel:[0,0,1]
	global_store_dword v[50:51], v38, off offset:56
	v_mov_b32_e32 v38, v151
	s_waitcnt vmcnt(15)
	v_lshlrev_b32_e32 v36, 16, v236
	v_and_b32_e32 v37, 0xffff0000, v236
	v_pk_fma_f32 v[18:19], v[66:67], v[18:19], v[36:37] op_sel_hi:[0,1,1]
	v_mul_f32_e32 v18, 0x41800000, v18
	v_mul_f32_e32 v19, 0x41800000, v19
	v_cvt_pk_fp8_f32 v38, v18, v19
	v_lshlrev_b32_e32 v34, 16, v237
	v_and_b32_e32 v35, 0xffff0000, v237
	v_pk_fma_f32 v[18:19], v[66:67], v[20:21], v[34:35] op_sel_hi:[0,1,1]
	v_mul_f32_e32 v18, 0x41800000, v18
	v_mul_f32_e32 v19, 0x41800000, v19
	v_cvt_pk_fp8_f32 v38, v18, v19 op_sel:[0,0,1]
	v_mov_b32_e32 v34, v151
	global_store_dword v[50:51], v38, off offset:64
	s_waitcnt vmcnt(15)
	v_lshlrev_b32_e32 v20, 16, v238
	v_and_b32_e32 v21, 0xffff0000, v238
	v_pk_fma_f32 v[20:21], v[66:67], v[22:23], v[20:21] op_sel_hi:[0,1,1]
	v_mul_f32_e32 v20, 0x41800000, v20
	v_mul_f32_e32 v21, 0x41800000, v21
	v_cvt_pk_fp8_f32 v34, v20, v21
	v_lshlrev_b32_e32 v18, 16, v239
	v_and_b32_e32 v19, 0xffff0000, v239
	v_pk_fma_f32 v[18:19], v[66:67], v[24:25], v[18:19] op_sel_hi:[0,1,1]
	v_mul_f32_e32 v18, 0x41800000, v18
	v_mul_f32_e32 v19, 0x41800000, v19
	v_cvt_pk_fp8_f32 v34, v18, v19 op_sel:[0,0,1]
	v_mov_b32_e32 v22, v151
	global_store_dword v[50:51], v34, off offset:72
	s_waitcnt vmcnt(15)
	v_lshlrev_b32_e32 v20, 16, v240
	v_and_b32_e32 v21, 0xffff0000, v240
	v_pk_fma_f32 v[20:21], v[66:67], v[26:27], v[20:21] op_sel_hi:[0,1,1]
	v_mul_f32_e32 v20, 0x41800000, v20
	v_mul_f32_e32 v21, 0x41800000, v21
	v_cvt_pk_fp8_f32 v22, v20, v21
	v_lshlrev_b32_e32 v18, 16, v241
	v_and_b32_e32 v19, 0xffff0000, v241
	v_pk_fma_f32 v[18:19], v[66:67], v[28:29], v[18:19] op_sel_hi:[0,1,1]
	v_mul_f32_e32 v18, 0x41800000, v18
	v_mul_f32_e32 v19, 0x41800000, v19
	v_cvt_pk_fp8_f32 v22, v18, v19 op_sel:[0,0,1]
	global_store_dword v[50:51], v22, off offset:80
	v_mov_b32_e32 v22, v151
	s_waitcnt vmcnt(15)
	v_lshlrev_b32_e32 v20, 16, v242
	v_and_b32_e32 v21, 0xffff0000, v242
	v_pk_fma_f32 v[20:21], v[66:67], v[30:31], v[20:21] op_sel_hi:[0,1,1]
	v_mul_f32_e32 v20, 0x41800000, v20
	v_mul_f32_e32 v21, 0x41800000, v21
	v_cvt_pk_fp8_f32 v22, v20, v21
	v_lshlrev_b32_e32 v18, 16, v243
	v_and_b32_e32 v19, 0xffff0000, v243
	v_pk_fma_f32 v[18:19], v[66:67], v[32:33], v[18:19] op_sel_hi:[0,1,1]
	v_mul_f32_e32 v18, 0x41800000, v18
	v_mul_f32_e32 v19, 0x41800000, v19
	v_cvt_pk_fp8_f32 v22, v18, v19 op_sel:[0,0,1]
	global_store_dword v[50:51], v22, off offset:88
	v_mov_b32_e32 v22, v151
	s_waitcnt vmcnt(15)
	v_lshlrev_b32_e32 v20, 16, v246
	v_and_b32_e32 v21, 0xffff0000, v246
	v_pk_fma_f32 v[2:3], v[66:67], v[2:3], v[20:21] op_sel_hi:[0,1,1]
	v_mul_f32_e32 v2, 0x41800000, v2
	v_mul_f32_e32 v3, 0x41800000, v3
	v_cvt_pk_fp8_f32 v22, v2, v3
	v_lshlrev_b32_e32 v18, 16, v247
	v_and_b32_e32 v19, 0xffff0000, v247
	v_pk_fma_f32 v[2:3], v[66:67], v[4:5], v[18:19] op_sel_hi:[0,1,1]
	v_mul_f32_e32 v2, 0x41800000, v2
	v_mul_f32_e32 v3, 0x41800000, v3
	v_cvt_pk_fp8_f32 v22, v2, v3 op_sel:[0,0,1]
	v_mov_b32_e32 v18, v151
	global_store_dword v[50:51], v22, off offset:96
	s_waitcnt vmcnt(15)
	v_lshlrev_b32_e32 v4, 16, v248
	v_and_b32_e32 v5, 0xffff0000, v248
	v_pk_fma_f32 v[4:5], v[66:67], v[6:7], v[4:5] op_sel_hi:[0,1,1]
	v_mul_f32_e32 v4, 0x41800000, v4
	v_mul_f32_e32 v5, 0x41800000, v5
	v_cvt_pk_fp8_f32 v18, v4, v5
	v_lshlrev_b32_e32 v2, 16, v249
	v_and_b32_e32 v3, 0xffff0000, v249
	v_pk_fma_f32 v[2:3], v[66:67], v[8:9], v[2:3] op_sel_hi:[0,1,1]
	v_mul_f32_e32 v2, 0x41800000, v2
	v_mul_f32_e32 v3, 0x41800000, v3
	v_cvt_pk_fp8_f32 v18, v2, v3 op_sel:[0,0,1]
	v_mov_b32_e32 v6, v151
	global_store_dword v[50:51], v18, off offset:104
	s_waitcnt vmcnt(15)
	v_lshlrev_b32_e32 v4, 16, v250
	v_and_b32_e32 v5, 0xffff0000, v250
	v_pk_fma_f32 v[4:5], v[66:67], v[10:11], v[4:5] op_sel_hi:[0,1,1]
	v_mul_f32_e32 v4, 0x41800000, v4
	v_mul_f32_e32 v5, 0x41800000, v5
	v_cvt_pk_fp8_f32 v6, v4, v5
	v_lshlrev_b32_e32 v2, 16, v251
	v_and_b32_e32 v3, 0xffff0000, v251
	v_pk_fma_f32 v[2:3], v[66:67], v[12:13], v[2:3] op_sel_hi:[0,1,1]
	v_mul_f32_e32 v2, 0x41800000, v2
	v_mul_f32_e32 v3, 0x41800000, v3
	v_cvt_pk_fp8_f32 v6, v2, v3 op_sel:[0,0,1]
	global_store_dword v[50:51], v6, off offset:112
	v_mov_b32_e32 v6, v151
	s_waitcnt vmcnt(15)
	v_lshlrev_b32_e32 v4, 16, v252
	v_and_b32_e32 v5, 0xffff0000, v252
	v_pk_fma_f32 v[4:5], v[66:67], v[14:15], v[4:5] op_sel_hi:[0,1,1]
	v_mul_f32_e32 v4, 0x41800000, v4
	v_mul_f32_e32 v5, 0x41800000, v5
	v_cvt_pk_fp8_f32 v6, v4, v5
	v_lshlrev_b32_e32 v2, 16, v253
	v_and_b32_e32 v3, 0xffff0000, v253
	v_pk_fma_f32 v[2:3], v[66:67], v[16:17], v[2:3] op_sel_hi:[0,1,1]
	v_mul_f32_e32 v2, 0x41800000, v2
	v_mul_f32_e32 v3, 0x41800000, v3
	v_cvt_pk_fp8_f32 v6, v2, v3 op_sel:[0,0,1]
	global_store_dword v[50:51], v6, off offset:120
	s_cbranch_vccnz .LBB0_837
